# loop-edge SALU rotation in all three GEMM K-loops (head/tail pointer and tile-select SALU issued inside the last compute segment)
# baseline (speedup 1.0000x reference)
; #define PG8_STAGE(bufoff, gbase, voff) do { _Pragma("unroll") for (int _i = 0; _i < 2; ++_i) \
;         __builtin_amdgcn_global_load_lds((const unsigned*)((const char*)(gbase) + (voff)[_i]), (PG8_LAS unsigned*)(lds + (bufoff) + ldsw + _i * 8192), 16, 0, 0); } while (0)
; #define PG8_LDA(dst, b, h) do { _Pragma("unroll") for (int m = 0; m < 4; ++m) _Pragma("unroll") for (int k = 0; k < 2; ++k) dst[m][k] = *(const PG8_LAS bf16x8*)(lds + PG8_SA(b, h) + aoff + m * 2048 + k * 1024); } while (0)
; #define PG8_LDB(dst, b, h) do { _Pragma("unroll") for (int n = 0; n < 2; ++n) _Pragma("unroll") for (int k = 0; k < 2; ++k) dst[n][k] = *(const PG8_LAS bf16x8*)(lds + PG8_SB(b, h) + boff + n * 2048 + k * 1024); } while (0)
; #define PG8_SCHED __builtin_amdgcn_sched_barrier(0)
; template <class Epi, class Sched, bool ALIGN_EPI = false, bool SP2 = false>
; __device__ __forceinline__ void gemm_phase(PG8_LAS unsigned char* lds, const Gemm g, const Sched& S, const Epi& E) {
;     ...
;         const bool has_next = S.next(ui + 1, nxt);
;         const char* nA = has_next ? (const char*)g.A + (size_t)nxt.pm * tstep : cA; const char* nB = has_next ? (const char*)g.Bt + (size_t)nxt.pn * tstep : cB;
;         for (int t = 0; t < nt; t += 2) {
;             const bool last = (t == nt - 2);
;             const char* a1 = cA + (size_t)(t + 1) * kstep;
;             const char* a2 = last ? nA : cA + (size_t)(t + 2) * kstep; const char* b2 = last ? nB : cB + (size_t)(t + 2) * kstep;
;             const char* a3 = a2 + kstep; const char* b3 = b2 + kstep;
;             if (last && has_next) S.a_ready(nxt);
;             if constexpr (SP2) {
;             PG8_LDB(B0, 0, 0); PG8_LDB(B1, 0, 1); PG8_SCHED; PG8_LDA(At, 0, 0); PG8_STAGE(PG8_SA(1, 1), a1 + hstep, voffA);
;     ...
; #pragma unroll
;         for (int a = 0; a < 2; ++a)
; #pragma unroll
;             for (int b = 0; b < 2; ++b)
; #pragma unroll
;                 for (int m = 0; m < 4; ++m)
; #pragma unroll
;                     for (int n = 0; n < 2; ++n) acc[a][b][m][n] = (f32x4){0.f, 0.f, 0.f, 0.f};
;         cur = nxt; cA = nA; cB = nB; ++ui;
.LBB0_81:
	s_ashr_i32 s65, s64, 31
	s_lshl_b64 s[28:29], s[64:65], s63
	s_add_u32 s66, s21, s28
	s_addc_u32 s67, s20, s29
	s_and_b64 s[28:29], s[42:43], exec
	s_cselect_b32 s65, s67, s45
	s_cselect_b32 s92, s66, s44
	s_ashr_i32 s61, s60, 31
	s_lshl_b64 s[28:29], s[60:61], s63
	v_readlane_b32 s12, v255, 27
	s_add_u32 s88, s12, s28
	s_addc_u32 s89, s62, s29
	s_and_b64 s[28:29], s[42:43], exec
	s_cselect_b32 s61, s89, s47
	s_cselect_b32 s93, s88, s46
	s_add_u32 s44, s44, 0x80
	s_addc_u32 s45, s45, 0
	s_add_u32 vcc_lo, s46, 0x100
	v_mov_b32_e32 v0, 0
	s_addc_u32 vcc_hi, s47, 0
	s_mov_b32 s46, 0
	v_mov_b32_e32 v1, v0
	v_mov_b32_e32 v2, v0
	v_mov_b32_e32 v3, v0
	v_mov_b32_e32 v4, v0
	v_mov_b32_e32 v5, v0
	v_mov_b32_e32 v6, v0
	v_mov_b32_e32 v7, v0
	v_mov_b32_e32 v16, v0
	v_mov_b32_e32 v17, v0
	v_mov_b32_e32 v18, v0
	v_mov_b32_e32 v19, v0
	v_mov_b32_e32 v20, v0
	v_mov_b32_e32 v21, v0
	v_mov_b32_e32 v22, v0
	v_mov_b32_e32 v23, v0
	v_mov_b32_e32 v32, v0
	v_mov_b32_e32 v33, v0
	v_mov_b32_e32 v34, v0
	v_mov_b32_e32 v35, v0
	v_mov_b32_e32 v36, v0
	v_mov_b32_e32 v37, v0
	v_mov_b32_e32 v38, v0
	v_mov_b32_e32 v39, v0
	v_mov_b32_e32 v48, v0
	v_mov_b32_e32 v49, v0
	v_mov_b32_e32 v50, v0
	v_mov_b32_e32 v51, v0
	v_mov_b32_e32 v52, v0
	v_mov_b32_e32 v53, v0
	v_mov_b32_e32 v54, v0
	v_mov_b32_e32 v55, v0
	v_mov_b32_e32 v8, v0
	v_mov_b32_e32 v9, v0
	v_mov_b32_e32 v10, v0
	v_mov_b32_e32 v11, v0
	v_mov_b32_e32 v12, v0
	v_mov_b32_e32 v13, v0
	v_mov_b32_e32 v14, v0
	v_mov_b32_e32 v15, v0
	v_mov_b32_e32 v24, v0
	v_mov_b32_e32 v25, v0
	v_mov_b32_e32 v26, v0
	v_mov_b32_e32 v27, v0
	v_mov_b32_e32 v28, v0
	v_mov_b32_e32 v29, v0
	v_mov_b32_e32 v30, v0
	v_mov_b32_e32 v31, v0
	v_mov_b32_e32 v40, v0
	v_mov_b32_e32 v41, v0
	v_mov_b32_e32 v42, v0
	v_mov_b32_e32 v43, v0
	v_mov_b32_e32 v44, v0
	v_mov_b32_e32 v45, v0
	v_mov_b32_e32 v46, v0
	v_mov_b32_e32 v47, v0
	v_mov_b32_e32 v72, v0
	v_mov_b32_e32 v73, v0
	v_mov_b32_e32 v74, v0
	v_mov_b32_e32 v75, v0
	v_mov_b32_e32 v76, v0
	v_mov_b32_e32 v77, v0
	v_mov_b32_e32 v78, v0
	v_mov_b32_e32 v79, v0
	v_mov_b32_e32 v80, v0
	v_mov_b32_e32 v81, v0
	v_mov_b32_e32 v82, v0
	v_mov_b32_e32 v83, v0
	v_mov_b32_e32 v84, v0
	v_mov_b32_e32 v85, v0
	v_mov_b32_e32 v86, v0
	v_mov_b32_e32 v87, v0
	v_mov_b32_e32 v96, v0
	v_mov_b32_e32 v97, v0
	v_mov_b32_e32 v98, v0
	v_mov_b32_e32 v99, v0
	v_mov_b32_e32 v100, v0
	v_mov_b32_e32 v101, v0
	v_mov_b32_e32 v102, v0
	v_mov_b32_e32 v103, v0
	v_mov_b32_e32 v112, v0
	v_mov_b32_e32 v113, v0
	v_mov_b32_e32 v114, v0
	v_mov_b32_e32 v115, v0
	v_mov_b32_e32 v116, v0
	v_mov_b32_e32 v117, v0
	v_mov_b32_e32 v118, v0
	v_mov_b32_e32 v119, v0
	v_mov_b32_e32 v128, v0
	v_mov_b32_e32 v129, v0
	v_mov_b32_e32 v130, v0
	v_mov_b32_e32 v131, v0
	v_mov_b32_e32 v132, v0
	v_mov_b32_e32 v133, v0
	v_mov_b32_e32 v134, v0
	v_mov_b32_e32 v135, v0
	v_mov_b32_e32 v88, v0
	v_mov_b32_e32 v89, v0
	v_mov_b32_e32 v90, v0
	v_mov_b32_e32 v91, v0
	v_mov_b32_e32 v92, v0
	v_mov_b32_e32 v93, v0
	v_mov_b32_e32 v94, v0
	v_mov_b32_e32 v95, v0
	v_mov_b32_e32 v104, v0
	v_mov_b32_e32 v105, v0
	v_mov_b32_e32 v106, v0
	v_mov_b32_e32 v107, v0
	v_mov_b32_e32 v108, v0
	v_mov_b32_e32 v109, v0
	v_mov_b32_e32 v110, v0
	v_mov_b32_e32 v111, v0
	v_mov_b32_e32 v120, v0
	v_mov_b32_e32 v121, v0
	v_mov_b32_e32 v122, v0
	v_mov_b32_e32 v123, v0
	v_mov_b32_e32 v124, v0
	v_mov_b32_e32 v125, v0
	v_mov_b32_e32 v126, v0
	v_mov_b32_e32 v127, v0
	v_mov_b32_e32 v136, v0
	v_mov_b32_e32 v137, v0
	v_mov_b32_e32 v138, v0
	v_mov_b32_e32 v139, v0
	v_mov_b32_e32 v140, v0
	v_mov_b32_e32 v141, v0
	v_mov_b32_e32 v142, v0
	v_mov_b32_e32 v143, v0
	s_nop 0
	s_nop 0
	s_nop 0
	s_nop 0
	s_nop 0
	s_nop 0
	s_nop 0
	s_nop 0
	v_add_u32_e32 v204, 0x10000, v235
	v_add_u32_e32 v205, 0x14000, v235
	v_add_u32_e32 v206, 0x18000, v235
	v_add_u32_e32 v207, 0x1c000, v235
	s_add_i32 s28, s46, 2
	s_add_u32 s29, s44, 0x80
	s_addc_u32 s47, s45, 0
	s_add_i32 s12, 0, 0x10000
	s_cmp_eq_u32 s24, s46
	s_cselect_b32 s47, s65, s47
	s_cselect_b32 s46, s92, s29
	s_cselect_b32 s73, s61, vcc_hi
	s_cselect_b32 s72, s93, vcc_lo
	s_add_i32 s29, 0, 0x14000
.LBB0_82:
	ds_read_b128 v[56:59], v204
	ds_read_b128 v[60:63], v204 offset:1024
	ds_read_b128 v[64:67], v204 offset:2048
	ds_read_b128 v[68:71], v204 offset:3072
	ds_read_b128 v[144:147], v205
	ds_read_b128 v[148:151], v205 offset:1024
	ds_read_b128 v[152:155], v205 offset:2048
	ds_read_b128 v[156:159], v205 offset:3072
	s_add_i32 m0, s70, 0xc000
	ds_read_b128 v[160:163], v237
	ds_read_b128 v[164:167], v237 offset:1024
	ds_read_b128 v[168:171], v237 offset:2048
	ds_read_b128 v[172:175], v237 offset:3072
	ds_read_b128 v[186:189], v237 offset:4096
	ds_read_b128 v[190:193], v237 offset:5120
	ds_read_b128 v[196:199], v237 offset:6144
	ds_read_b128 v[200:203], v237 offset:7168
	global_load_lds_dwordx4 v182, s[44:45]
	s_add_i32 m0, s70, 0xe000
	s_nop 0
	global_load_lds_dwordx4 v184, s[44:45]
	s_waitcnt vmcnt(8)
	s_waitcnt lgkmcnt(0)
	s_barrier
; #define PG8_STAGE(bufoff, gbase, voff) do { _Pragma("unroll") for (int _i = 0; _i < 2; ++_i) \
;         __builtin_amdgcn_global_load_lds((const unsigned*)((const char*)(gbase) + (voff)[_i]), (PG8_LAS unsigned*)(lds + (bufoff) + ldsw + _i * 8192), 16, 0, 0); } while (0)
; #define PG8_LDA(dst, b, h) do { _Pragma("unroll") for (int m = 0; m < 4; ++m) _Pragma("unroll") for (int k = 0; k < 2; ++k) dst[m][k] = *(const PG8_LAS bf16x8*)(lds + PG8_SA(b, h) + aoff + m * 2048 + k * 1024); } while (0)
; #define PG8_LDB(dst, b, h) do { _Pragma("unroll") for (int n = 0; n < 2; ++n) _Pragma("unroll") for (int k = 0; k < 2; ++k) dst[n][k] = *(const PG8_LAS bf16x8*)(lds + PG8_SB(b, h) + boff + n * 2048 + k * 1024); } while (0)
; #define PG8_MMA(ai, bj, At, Bt) do { __builtin_amdgcn_s_setprio(1); _Pragma("unroll") for (int m = 0; m < 4; ++m) _Pragma("unroll") for (int n = 0; n < 2; ++n) _Pragma("unroll") for (int k = 0; k < 2; ++k) \
;         acc[ai][bj][m][n] = __builtin_amdgcn_mfma_f32_16x16x32_bf16(Bt[n][k], At[m][k], acc[ai][bj][m][n], 0, 0, 0); __builtin_amdgcn_s_setprio(0); } while (0)
; #define PG8_WAIT_V(n) asm volatile("s_waitcnt vmcnt(" #n ")" ::: "memory")
; #define PG8_WAIT_L(n) asm volatile("s_waitcnt lgkmcnt(" #n ")" ::: "memory")
; #define PG8_BAR __builtin_amdgcn_s_barrier()
; #define PG8_SCHED __builtin_amdgcn_sched_barrier(0)
; template <class Epi, class Sched, bool ALIGN_EPI = false, bool SP2 = false>
; __device__ __forceinline__ void gemm_phase(PG8_LAS unsigned char* lds, const Gemm g, const Sched& S, const Epi& E) {
;     ...
;             PG8_LDB(B0, 0, 0); PG8_LDB(B1, 0, 1); PG8_SCHED; PG8_LDA(At, 0, 0); PG8_STAGE(PG8_SA(1, 1), a1 + hstep, voffA);
;             PG8_WAIT_V(8); PG8_WAIT_L(0); PG8_BAR; PG8_MMA(0, 0, At, B0); PG8_MMA(0, 1, At, B1); PG8_BAR; PG8_SCHED;
;             PG8_LDA(At, 0, 1); PG8_STAGE(PG8_SB(0, 0), b2, voffB); PG8_STAGE(PG8_SB(0, 1), b2 + hstep, voffB); PG8_STAGE(PG8_SA(0, 0), a2, voffA);
;             PG8_WAIT_V(8); PG8_WAIT_L(0); PG8_BAR; PG8_MMA(1, 0, At, B0); PG8_MMA(1, 1, At, B1); PG8_BAR; PG8_SCHED;
	s_setprio 1
	s_waitcnt lgkmcnt(0)
	v_mfma_f32_16x16x32_bf16 v[140:143], v[56:59], v[160:163], v[140:143]
	v_mfma_f32_16x16x32_bf16 v[136:139], v[64:67], v[160:163], v[136:139]
	v_mfma_f32_16x16x32_bf16 v[124:127], v[56:59], v[168:171], v[124:127]
	v_mfma_f32_16x16x32_bf16 v[120:123], v[64:67], v[168:171], v[120:123]
	v_mfma_f32_16x16x32_bf16 v[108:111], v[56:59], v[186:189], v[108:111]
	v_mfma_f32_16x16x32_bf16 v[104:107], v[64:67], v[186:189], v[104:107]
	v_mfma_f32_16x16x32_bf16 v[92:95], v[56:59], v[196:199], v[92:95]
	v_mfma_f32_16x16x32_bf16 v[88:91], v[64:67], v[196:199], v[88:91]
	v_mfma_f32_16x16x32_bf16 v[140:143], v[60:63], v[164:167], v[140:143]
	v_mfma_f32_16x16x32_bf16 v[136:139], v[68:71], v[164:167], v[136:139]
	v_mfma_f32_16x16x32_bf16 v[124:127], v[60:63], v[172:175], v[124:127]
	v_mfma_f32_16x16x32_bf16 v[120:123], v[68:71], v[172:175], v[120:123]
	v_mfma_f32_16x16x32_bf16 v[108:111], v[60:63], v[190:193], v[108:111]
	v_mfma_f32_16x16x32_bf16 v[104:107], v[68:71], v[190:193], v[104:107]
	v_mfma_f32_16x16x32_bf16 v[92:95], v[60:63], v[200:203], v[92:95]
	v_mfma_f32_16x16x32_bf16 v[88:91], v[68:71], v[200:203], v[88:91]
	s_setprio 0
	s_setprio 1
	v_mfma_f32_16x16x32_bf16 v[132:135], v[144:147], v[160:163], v[132:135]
	v_mfma_f32_16x16x32_bf16 v[128:131], v[152:155], v[160:163], v[128:131]
	v_mfma_f32_16x16x32_bf16 v[116:119], v[144:147], v[168:171], v[116:119]
	v_mfma_f32_16x16x32_bf16 v[112:115], v[152:155], v[168:171], v[112:115]
	v_mfma_f32_16x16x32_bf16 v[100:103], v[144:147], v[186:189], v[100:103]
	v_mfma_f32_16x16x32_bf16 v[96:99], v[152:155], v[186:189], v[96:99]
	v_mfma_f32_16x16x32_bf16 v[84:87], v[144:147], v[196:199], v[84:87]
	v_mfma_f32_16x16x32_bf16 v[80:83], v[152:155], v[196:199], v[80:83]
	v_mfma_f32_16x16x32_bf16 v[132:135], v[148:151], v[164:167], v[132:135]
	v_mfma_f32_16x16x32_bf16 v[128:131], v[156:159], v[164:167], v[128:131]
	v_mfma_f32_16x16x32_bf16 v[116:119], v[148:151], v[172:175], v[116:119]
	v_mfma_f32_16x16x32_bf16 v[112:115], v[156:159], v[172:175], v[112:115]
	v_mfma_f32_16x16x32_bf16 v[100:103], v[148:151], v[190:193], v[100:103]
	v_mfma_f32_16x16x32_bf16 v[96:99], v[156:159], v[190:193], v[96:99]
	v_mfma_f32_16x16x32_bf16 v[84:87], v[148:151], v[200:203], v[84:87]
	v_mfma_f32_16x16x32_bf16 v[80:83], v[156:159], v[200:203], v[80:83]
	s_setprio 0
	s_barrier
	s_add_i32 s12, s12, s2
	s_mov_b32 m0, s12
	ds_read_b128 v[160:163], v237 offset:16384
	ds_read_b128 v[164:167], v237 offset:17408
	ds_read_b128 v[168:171], v237 offset:18432
	ds_read_b128 v[172:175], v237 offset:19456
	ds_read_b128 v[186:189], v237 offset:20480
	ds_read_b128 v[190:193], v237 offset:21504
	ds_read_b128 v[196:199], v237 offset:22528
	ds_read_b128 v[200:203], v237 offset:23552
	global_load_lds_dwordx4 v194, s[72:73]
	s_add_i32 m0, s12, 0x2000
	s_add_u32 s98, s72, 0x80
	s_addc_u32 s99, s73, 0
	s_add_i32 s12, s29, s2
	global_load_lds_dwordx4 v176, s[72:73]
	s_mov_b32 m0, s12
	s_add_u32 s72, s72, s22
	s_addc_u32 s73, s73, 0
	s_add_u32 s100, s46, 0x80
	s_addc_u32 s101, s47, 0
	global_load_lds_dwordx4 v194, s[72:73]
	s_add_i32 m0, s12, 0x2000
	s_nop 0
	global_load_lds_dwordx4 v176, s[72:73]
	s_mov_b32 m0, s70
	s_nop 0
	global_load_lds_dwordx4 v180, s[46:47]
	s_mov_b32 m0, s71
	s_nop 0
	global_load_lds_dwordx4 v178, s[46:47]
	s_waitcnt vmcnt(8)
	s_waitcnt lgkmcnt(0)
	s_barrier
	s_setprio 1
	s_waitcnt lgkmcnt(0)
	v_mfma_f32_16x16x32_bf16 v[76:79], v[56:59], v[160:163], v[76:79]
	v_mfma_f32_16x16x32_bf16 v[72:75], v[64:67], v[160:163], v[72:75]
	v_mfma_f32_16x16x32_bf16 v[44:47], v[56:59], v[168:171], v[44:47]
	v_mfma_f32_16x16x32_bf16 v[40:43], v[64:67], v[168:171], v[40:43]
	v_mfma_f32_16x16x32_bf16 v[28:31], v[56:59], v[186:189], v[28:31]
	v_mfma_f32_16x16x32_bf16 v[24:27], v[64:67], v[186:189], v[24:27]
	v_mfma_f32_16x16x32_bf16 v[12:15], v[56:59], v[196:199], v[12:15]
	v_mfma_f32_16x16x32_bf16 v[8:11], v[64:67], v[196:199], v[8:11]
	v_mfma_f32_16x16x32_bf16 v[76:79], v[60:63], v[164:167], v[76:79]
	v_mfma_f32_16x16x32_bf16 v[72:75], v[68:71], v[164:167], v[72:75]
	v_mfma_f32_16x16x32_bf16 v[44:47], v[60:63], v[172:175], v[44:47]
	v_mfma_f32_16x16x32_bf16 v[40:43], v[68:71], v[172:175], v[40:43]
	v_mfma_f32_16x16x32_bf16 v[28:31], v[60:63], v[190:193], v[28:31]
	v_mfma_f32_16x16x32_bf16 v[24:27], v[68:71], v[190:193], v[24:27]
	v_mfma_f32_16x16x32_bf16 v[12:15], v[60:63], v[200:203], v[12:15]
	v_mfma_f32_16x16x32_bf16 v[8:11], v[68:71], v[200:203], v[8:11]
	s_setprio 0
	s_setprio 1
	v_mfma_f32_16x16x32_bf16 v[52:55], v[144:147], v[160:163], v[52:55]
	v_mfma_f32_16x16x32_bf16 v[48:51], v[152:155], v[160:163], v[48:51]
	v_mfma_f32_16x16x32_bf16 v[36:39], v[144:147], v[168:171], v[36:39]
	v_mfma_f32_16x16x32_bf16 v[32:35], v[152:155], v[168:171], v[32:35]
	v_mfma_f32_16x16x32_bf16 v[20:23], v[144:147], v[186:189], v[20:23]
	v_mfma_f32_16x16x32_bf16 v[16:19], v[152:155], v[186:189], v[16:19]
	v_mfma_f32_16x16x32_bf16 v[4:7], v[144:147], v[196:199], v[4:7]
	v_mfma_f32_16x16x32_bf16 v[0:3], v[152:155], v[196:199], v[0:3]
	v_mfma_f32_16x16x32_bf16 v[52:55], v[148:151], v[164:167], v[52:55]
	v_mfma_f32_16x16x32_bf16 v[48:51], v[156:159], v[164:167], v[48:51]
	v_mfma_f32_16x16x32_bf16 v[36:39], v[148:151], v[172:175], v[36:39]
	v_mfma_f32_16x16x32_bf16 v[32:35], v[156:159], v[172:175], v[32:35]
	v_mfma_f32_16x16x32_bf16 v[20:23], v[148:151], v[190:193], v[20:23]
	v_mfma_f32_16x16x32_bf16 v[16:19], v[156:159], v[190:193], v[16:19]
	v_mfma_f32_16x16x32_bf16 v[4:7], v[148:151], v[200:203], v[4:7]
	v_mfma_f32_16x16x32_bf16 v[0:3], v[156:159], v[200:203], v[0:3]
	s_setprio 0
	s_barrier
; #define PG8_STAGE(bufoff, gbase, voff) do { _Pragma("unroll") for (int _i = 0; _i < 2; ++_i) \
;         __builtin_amdgcn_global_load_lds((const unsigned*)((const char*)(gbase) + (voff)[_i]), (PG8_LAS unsigned*)(lds + (bufoff) + ldsw + _i * 8192), 16, 0, 0); } while (0)
; #define PG8_LDA(dst, b, h) do { _Pragma("unroll") for (int m = 0; m < 4; ++m) _Pragma("unroll") for (int k = 0; k < 2; ++k) dst[m][k] = *(const PG8_LAS bf16x8*)(lds + PG8_SA(b, h) + aoff + m * 2048 + k * 1024); } while (0)
; #define PG8_LDB(dst, b, h) do { _Pragma("unroll") for (int n = 0; n < 2; ++n) _Pragma("unroll") for (int k = 0; k < 2; ++k) dst[n][k] = *(const PG8_LAS bf16x8*)(lds + PG8_SB(b, h) + boff + n * 2048 + k * 1024); } while (0)
; #define PG8_MMA(ai, bj, At, Bt) do { __builtin_amdgcn_s_setprio(1); _Pragma("unroll") for (int m = 0; m < 4; ++m) _Pragma("unroll") for (int n = 0; n < 2; ++n) _Pragma("unroll") for (int k = 0; k < 2; ++k) \
;         acc[ai][bj][m][n] = __builtin_amdgcn_mfma_f32_16x16x32_bf16(Bt[n][k], At[m][k], acc[ai][bj][m][n], 0, 0, 0); __builtin_amdgcn_s_setprio(0); } while (0)
; #define PG8_WAIT_V(n) asm volatile("s_waitcnt vmcnt(" #n ")" ::: "memory")
; #define PG8_WAIT_L(n) asm volatile("s_waitcnt lgkmcnt(" #n ")" ::: "memory")
; #define PG8_BAR __builtin_amdgcn_s_barrier()
; #define PG8_SCHED __builtin_amdgcn_sched_barrier(0)
; template <class Epi, class Sched, bool ALIGN_EPI = false, bool SP2 = false>
; __device__ __forceinline__ void gemm_phase(PG8_LAS unsigned char* lds, const Gemm g, const Sched& S, const Epi& E) {
;     ...
;         for (int t = 0; t < nt; t += 2) {
;             const bool last = (t == nt - 2);
;             const char* a1 = cA + (size_t)(t + 1) * kstep;
;             const char* a2 = last ? nA : cA + (size_t)(t + 2) * kstep; const char* b2 = last ? nB : cB + (size_t)(t + 2) * kstep;
;     ...
;             PG8_LDB(B0, 1, 0); PG8_LDB(B1, 1, 1); PG8_SCHED; PG8_LDA(At, 1, 0); PG8_STAGE(PG8_SA(0, 1), a2 + hstep, voffA);
;             PG8_WAIT_V(8); PG8_WAIT_L(0); PG8_BAR; PG8_MMA(0, 0, At, B0); PG8_MMA(0, 1, At, B1); PG8_BAR; PG8_SCHED;
;             PG8_LDA(At, 1, 1); PG8_STAGE(PG8_SB(1, 0), b3, voffB); PG8_STAGE(PG8_SB(1, 1), b3 + hstep, voffB); PG8_STAGE(PG8_SA(1, 0), a3, voffA);
;             PG8_WAIT_V(8); PG8_WAIT_L(0); PG8_BAR; PG8_MMA(1, 0, At, B0); PG8_MMA(1, 1, At, B1); PG8_BAR; PG8_SCHED;
	s_add_i32 s12, 0, 0x18000
	s_add_i32 s29, 0, 0x1c000
	ds_read_b128 v[56:59], v206
	ds_read_b128 v[60:63], v206 offset:1024
	ds_read_b128 v[64:67], v206 offset:2048
	ds_read_b128 v[68:71], v206 offset:3072
	ds_read_b128 v[144:147], v207
	ds_read_b128 v[148:151], v207 offset:1024
	ds_read_b128 v[152:155], v207 offset:2048
	ds_read_b128 v[156:159], v207 offset:3072
	s_add_u32 s46, s46, s22
	s_addc_u32 s47, s47, 0
	s_mov_b32 m0, s76
	ds_read_b128 v[160:163], v237 offset:32768
	ds_read_b128 v[164:167], v237 offset:33792
	ds_read_b128 v[168:171], v237 offset:34816
	ds_read_b128 v[172:175], v237 offset:35840
	ds_read_b128 v[186:189], v237 offset:36864
	ds_read_b128 v[190:193], v237 offset:37888
	ds_read_b128 v[196:199], v237 offset:38912
	ds_read_b128 v[200:203], v237 offset:39936
	global_load_lds_dwordx4 v180, s[46:47]
	s_mov_b32 m0, s77
	s_nop 0
	global_load_lds_dwordx4 v178, s[46:47]
	s_waitcnt vmcnt(8)
	s_waitcnt lgkmcnt(0)
	s_barrier
	s_setprio 1
	s_waitcnt lgkmcnt(0)
	v_mfma_f32_16x16x32_bf16 v[140:143], v[56:59], v[160:163], v[140:143]
	v_mfma_f32_16x16x32_bf16 v[136:139], v[64:67], v[160:163], v[136:139]
	v_mfma_f32_16x16x32_bf16 v[124:127], v[56:59], v[168:171], v[124:127]
	v_mfma_f32_16x16x32_bf16 v[120:123], v[64:67], v[168:171], v[120:123]
	v_mfma_f32_16x16x32_bf16 v[108:111], v[56:59], v[186:189], v[108:111]
	v_mfma_f32_16x16x32_bf16 v[104:107], v[64:67], v[186:189], v[104:107]
	v_mfma_f32_16x16x32_bf16 v[92:95], v[56:59], v[196:199], v[92:95]
	v_mfma_f32_16x16x32_bf16 v[88:91], v[64:67], v[196:199], v[88:91]
	v_mfma_f32_16x16x32_bf16 v[140:143], v[60:63], v[164:167], v[140:143]
	v_mfma_f32_16x16x32_bf16 v[136:139], v[68:71], v[164:167], v[136:139]
	v_mfma_f32_16x16x32_bf16 v[124:127], v[60:63], v[172:175], v[124:127]
	v_mfma_f32_16x16x32_bf16 v[120:123], v[68:71], v[172:175], v[120:123]
	v_mfma_f32_16x16x32_bf16 v[108:111], v[60:63], v[190:193], v[108:111]
	v_mfma_f32_16x16x32_bf16 v[104:107], v[68:71], v[190:193], v[104:107]
	v_mfma_f32_16x16x32_bf16 v[92:95], v[60:63], v[200:203], v[92:95]
	v_mfma_f32_16x16x32_bf16 v[88:91], v[68:71], v[200:203], v[88:91]
	s_setprio 0
	s_setprio 1
	v_mfma_f32_16x16x32_bf16 v[132:135], v[144:147], v[160:163], v[132:135]
	v_mfma_f32_16x16x32_bf16 v[128:131], v[152:155], v[160:163], v[128:131]
	v_mfma_f32_16x16x32_bf16 v[116:119], v[144:147], v[168:171], v[116:119]
	v_mfma_f32_16x16x32_bf16 v[112:115], v[152:155], v[168:171], v[112:115]
	v_mfma_f32_16x16x32_bf16 v[100:103], v[144:147], v[186:189], v[100:103]
	v_mfma_f32_16x16x32_bf16 v[96:99], v[152:155], v[186:189], v[96:99]
	v_mfma_f32_16x16x32_bf16 v[84:87], v[144:147], v[196:199], v[84:87]
	v_mfma_f32_16x16x32_bf16 v[80:83], v[152:155], v[196:199], v[80:83]
	v_mfma_f32_16x16x32_bf16 v[132:135], v[148:151], v[164:167], v[132:135]
	v_mfma_f32_16x16x32_bf16 v[128:131], v[156:159], v[164:167], v[128:131]
	v_mfma_f32_16x16x32_bf16 v[116:119], v[148:151], v[172:175], v[116:119]
	v_mfma_f32_16x16x32_bf16 v[112:115], v[156:159], v[172:175], v[112:115]
	v_mfma_f32_16x16x32_bf16 v[100:103], v[148:151], v[190:193], v[100:103]
	v_mfma_f32_16x16x32_bf16 v[96:99], v[156:159], v[190:193], v[96:99]
	v_mfma_f32_16x16x32_bf16 v[84:87], v[148:151], v[200:203], v[84:87]
	v_mfma_f32_16x16x32_bf16 v[80:83], v[156:159], v[200:203], v[80:83]
	s_setprio 0
	s_barrier
	s_add_i32 s12, s12, s2
	s_mov_b32 m0, s12
	ds_read_b128 v[160:163], v237 offset:49152
	ds_read_b128 v[164:167], v237 offset:50176
	ds_read_b128 v[168:171], v237 offset:51200
	ds_read_b128 v[172:175], v237 offset:52224
	ds_read_b128 v[186:189], v237 offset:53248
	ds_read_b128 v[190:193], v237 offset:54272
	ds_read_b128 v[196:199], v237 offset:55296
	ds_read_b128 v[200:203], v237 offset:56320
	global_load_lds_dwordx4 v194, s[98:99]
	s_add_i32 m0, s12, 0x2000
	s_add_i32 s12, s29, s2
	s_add_u32 s72, s72, 0x80
	s_addc_u32 s73, s73, 0
	global_load_lds_dwordx4 v176, s[98:99]
	s_mov_b32 m0, s12
	s_nop 0
	global_load_lds_dwordx4 v194, s[72:73]
	s_add_i32 m0, s12, 0x2000
	s_nop 0
	global_load_lds_dwordx4 v176, s[72:73]
	s_mov_b32 m0, s48
	s_nop 0
	global_load_lds_dwordx4 v180, s[100:101]
	s_mov_b32 m0, s49
	s_nop 0
	global_load_lds_dwordx4 v178, s[100:101]
	s_waitcnt vmcnt(8)
	s_waitcnt lgkmcnt(0)
	s_barrier
	s_setprio 1
	s_waitcnt lgkmcnt(0)
	v_mfma_f32_16x16x32_bf16 v[76:79], v[56:59], v[160:163], v[76:79]
	v_mfma_f32_16x16x32_bf16 v[72:75], v[64:67], v[160:163], v[72:75]
	v_mfma_f32_16x16x32_bf16 v[44:47], v[56:59], v[168:171], v[44:47]
	v_mfma_f32_16x16x32_bf16 v[40:43], v[64:67], v[168:171], v[40:43]
	v_mfma_f32_16x16x32_bf16 v[28:31], v[56:59], v[186:189], v[28:31]
	v_mfma_f32_16x16x32_bf16 v[24:27], v[64:67], v[186:189], v[24:27]
	v_mfma_f32_16x16x32_bf16 v[12:15], v[56:59], v[196:199], v[12:15]
	v_mfma_f32_16x16x32_bf16 v[8:11], v[64:67], v[196:199], v[8:11]
	v_mfma_f32_16x16x32_bf16 v[76:79], v[60:63], v[164:167], v[76:79]
	v_mfma_f32_16x16x32_bf16 v[72:75], v[68:71], v[164:167], v[72:75]
	v_mfma_f32_16x16x32_bf16 v[44:47], v[60:63], v[172:175], v[44:47]
	v_mfma_f32_16x16x32_bf16 v[40:43], v[68:71], v[172:175], v[40:43]
	v_mfma_f32_16x16x32_bf16 v[28:31], v[60:63], v[190:193], v[28:31]
	v_mfma_f32_16x16x32_bf16 v[24:27], v[68:71], v[190:193], v[24:27]
	v_mfma_f32_16x16x32_bf16 v[12:15], v[60:63], v[200:203], v[12:15]
	v_mfma_f32_16x16x32_bf16 v[8:11], v[68:71], v[200:203], v[8:11]
	s_setprio 0
	s_setprio 1
	v_mfma_f32_16x16x32_bf16 v[52:55], v[144:147], v[160:163], v[52:55]
	s_add_u32 s44, s44, 0x100
	v_mfma_f32_16x16x32_bf16 v[48:51], v[152:155], v[160:163], v[48:51]
	s_addc_u32 s45, s45, 0
	v_mfma_f32_16x16x32_bf16 v[36:39], v[144:147], v[168:171], v[36:39]
	s_add_u32 vcc_lo, vcc_lo, 0x100
	v_mfma_f32_16x16x32_bf16 v[32:35], v[152:155], v[168:171], v[32:35]
	s_addc_u32 vcc_hi, vcc_hi, 0
	v_mfma_f32_16x16x32_bf16 v[20:23], v[144:147], v[186:189], v[20:23]
	s_mov_b32 s98, s28
	v_mfma_f32_16x16x32_bf16 v[16:19], v[152:155], v[186:189], v[16:19]
	s_add_i32 s28, s98, 2
	v_mfma_f32_16x16x32_bf16 v[4:7], v[144:147], v[196:199], v[4:7]
	s_add_u32 s29, s44, 0x80
	v_mfma_f32_16x16x32_bf16 v[0:3], v[152:155], v[196:199], v[0:3]
	s_addc_u32 s47, s45, 0
	v_mfma_f32_16x16x32_bf16 v[52:55], v[148:151], v[164:167], v[52:55]
	s_add_i32 s12, 0, 0x10000
	v_mfma_f32_16x16x32_bf16 v[48:51], v[156:159], v[164:167], v[48:51]
	s_cmp_eq_u32 s24, s98
	v_mfma_f32_16x16x32_bf16 v[36:39], v[148:151], v[172:175], v[36:39]
	s_cselect_b32 s47, s65, s47
	v_mfma_f32_16x16x32_bf16 v[32:35], v[156:159], v[172:175], v[32:35]
	s_cselect_b32 s46, s92, s29
	v_mfma_f32_16x16x32_bf16 v[20:23], v[148:151], v[190:193], v[20:23]
	s_cselect_b32 s73, s61, vcc_hi
	v_mfma_f32_16x16x32_bf16 v[16:19], v[156:159], v[190:193], v[16:19]
	s_cselect_b32 s72, s93, vcc_lo
	v_mfma_f32_16x16x32_bf16 v[4:7], v[148:151], v[200:203], v[4:7]
	s_add_i32 s29, 0, 0x14000
	v_mfma_f32_16x16x32_bf16 v[0:3], v[156:159], v[200:203], v[0:3]
	s_setprio 0
	s_barrier
	s_cmp_ge_u32 s98, s7
	s_cbranch_scc0 .LBB0_82
	s_and_b64 vcc, exec, s[50:51]
	s_cbranch_vccz .LBB0_85
	s_barrier
